# DF unit: gate rows of the epilogue touched (one dword per line) in the unit prologue so the epilogue reads hit the L2
# baseline (speedup 1.0000x reference)
.LBB0_385:
	s_and_b64 vcc, exec, s[2:3]
	s_cbranch_vccz .LBB0_300
	s_lshr_b32 s2, s97, 4
	s_bfe_u32 s22, s97, 0x40001
	s_and_b32 s2, s2, 2
	s_and_b32 s3, s97, 1
	s_ashr_i32 s6, s97, 6
	s_xor_b32 s8, s22, 15
	s_or_b32 s2, s2, s3
	s_xor_b32 s16, s2, 2
	s_lshl_b32 s2, s8, 7
	v_readlane_b32 s3, v255, 29
	s_ashr_i32 s7, s6, 31
	s_or_b32 s9, s2, s3
	s_lshl_b32 s10, s16, 18
	s_lshl_b64 s[2:3], s[6:7], 21
	v_mov_b32_e32 v216, v231
	s_add_u32 s17, s78, s2
	s_addc_u32 s18, s79, s3
	v_and_b32_e32 v218, 31, v216
	s_lshl_b32 s2, s16, 19
	v_or_b32_e32 v179, s9, v218
	s_add_u32 s2, s17, s2
	s_addc_u32 s3, s18, 0
	v_lshlrev_b32_e32 v0, 8, v179
	v_ashrrev_i32_e32 v219, 5, v216
	v_lshl_add_u64 v[2:3], s[2:3], 0, v[0:1]
	s_mov_b32 s85, s81
	v_lshl_add_u64 v[4:5], v[2:3], 0, s[84:85]
	v_lshlrev_b32_e32 v2, 3, v219
	v_ashrrev_i32_e32 v3, 31, v2
	v_lshl_add_u64 v[4:5], v[2:3], 1, v[4:5]
	s_brev_b32 s2, 32
	v_add_co_u32_e32 v6, vcc, s2, v4
	s_mov_b64 s[2:3], 0x4000000
	s_nop 0
	v_addc_co_u32_e32 v7, vcc, 0, v5, vcc
	global_load_dwordx4 v[112:115], v[6:7], off
	v_lshl_add_u64 v[4:5], v[4:5], 0, s[2:3]
	global_load_dwordx4 v[116:119], v[4:5], off offset:32
	global_load_dwordx4 v[120:123], v[4:5], off offset:64
	global_load_dwordx4 v[124:127], v[4:5], off offset:96
	s_lshl_b32 s2, s6, 5
	s_lshl_b32 s3, s16, 3
	v_readlane_b32 s4, v255, 26
	s_add_i32 s2, s2, 0
	s_lshl_b32 s4, s4, 2
	s_add_i32 s2, s2, s3
	s_add_i32 s2, s2, s4
	s_add_i32 s2, s2, 0x24a00
	v_mov_b32_e32 v0, s2
	ds_read_b32 v3, v0
	s_waitcnt vmcnt(2)
	v_lshlrev_b32_e32 v11, 16, v116
	v_lshlrev_b32_e32 v0, 16, v112
	v_and_b32_e32 v4, 0xffff0000, v112
	v_fma_f32 v0, v0, v0, 0
	v_lshlrev_b32_e32 v5, 16, v113
	v_fmac_f32_e32 v0, v4, v4
	v_and_b32_e32 v6, 0xffff0000, v113
	v_fmac_f32_e32 v0, v5, v5
	v_lshlrev_b32_e32 v7, 16, v114
	v_fmac_f32_e32 v0, v6, v6
	v_and_b32_e32 v8, 0xffff0000, v114
	v_fmac_f32_e32 v0, v7, v7
	v_lshlrev_b32_e32 v9, 16, v115
	v_fmac_f32_e32 v0, v8, v8
	v_and_b32_e32 v10, 0xffff0000, v115
	v_fmac_f32_e32 v0, v9, v9
	v_fmac_f32_e32 v0, v10, v10
	v_and_b32_e32 v12, 0xffff0000, v116
	v_fmac_f32_e32 v0, v11, v11
	v_lshlrev_b32_e32 v13, 16, v117
	v_fmac_f32_e32 v0, v12, v12
	v_and_b32_e32 v14, 0xffff0000, v117
	v_fmac_f32_e32 v0, v13, v13
	v_lshlrev_b32_e32 v15, 16, v118
	v_fmac_f32_e32 v0, v14, v14
	v_and_b32_e32 v16, 0xffff0000, v118
	v_fmac_f32_e32 v0, v15, v15
	v_lshlrev_b32_e32 v17, 16, v119
	v_fmac_f32_e32 v0, v16, v16
	v_and_b32_e32 v18, 0xffff0000, v119
	v_fmac_f32_e32 v0, v17, v17
	s_waitcnt vmcnt(1)
	v_lshlrev_b32_e32 v19, 16, v120
	v_fmac_f32_e32 v0, v18, v18
	v_and_b32_e32 v20, 0xffff0000, v120
	v_fmac_f32_e32 v0, v19, v19
	v_lshlrev_b32_e32 v21, 16, v121
	v_fmac_f32_e32 v0, v20, v20
	v_and_b32_e32 v22, 0xffff0000, v121
	v_fmac_f32_e32 v0, v21, v21
	v_lshlrev_b32_e32 v23, 16, v122
	v_fmac_f32_e32 v0, v22, v22
	v_and_b32_e32 v24, 0xffff0000, v122
	v_fmac_f32_e32 v0, v23, v23
	v_lshlrev_b32_e32 v25, 16, v123
	v_fmac_f32_e32 v0, v24, v24
	v_and_b32_e32 v26, 0xffff0000, v123
	v_fmac_f32_e32 v0, v25, v25
	s_waitcnt vmcnt(0)
	v_lshlrev_b32_e32 v27, 16, v124
	v_fmac_f32_e32 v0, v26, v26
	v_and_b32_e32 v28, 0xffff0000, v124
	v_fmac_f32_e32 v0, v27, v27
	v_lshlrev_b32_e32 v29, 16, v125
	v_fmac_f32_e32 v0, v28, v28
	v_and_b32_e32 v30, 0xffff0000, v125
	v_fmac_f32_e32 v0, v29, v29
	v_lshlrev_b32_e32 v31, 16, v126
	v_fmac_f32_e32 v0, v30, v30
	v_and_b32_e32 v32, 0xffff0000, v126
	v_fmac_f32_e32 v0, v31, v31
	v_lshlrev_b32_e32 v33, 16, v127
	v_fmac_f32_e32 v0, v32, v32
	v_and_b32_e32 v34, 0xffff0000, v127
	v_fmac_f32_e32 v0, v33, v33
	v_fmac_f32_e32 v0, v34, v34
	v_mov_b32_e32 v4, v0
	s_nop 1
	v_permlane32_swap_b32_e32 v0, v4
	v_add_f32_e32 v0, v0, v4
	s_nop 1
	v_mov_b32_dpp v4, v0 row_shr:1 row_mask:0xf bank_mask:0xf bound_ctrl:1
	v_max_f32_e32 v4, v4, v4
	v_max_f32_e32 v0, v0, v4
	s_nop 1
	v_mov_b32_dpp v4, v0 row_shr:2 row_mask:0xf bank_mask:0xf bound_ctrl:1
	v_max_f32_e32 v4, v4, v4
	v_max_f32_e32 v0, v0, v4
	s_nop 1
	v_mov_b32_dpp v4, v0 row_shr:4 row_mask:0xf bank_mask:0xf bound_ctrl:1
	v_max_f32_e32 v4, v4, v4
	v_max_f32_e32 v0, v0, v4
	s_nop 1
	v_mov_b32_dpp v4, v0 row_shr:8 row_mask:0xf bank_mask:0xf bound_ctrl:1
	v_max_f32_e32 v4, v4, v4
	v_max_f32_e32 v0, v0, v4
	v_mov_b32_e32 v4, v0
	s_nop 1
	v_permlane16_swap_b32_e32 v0, v4
	v_max_f32_e32 v4, v4, v4
	v_max_f32_e32 v0, v0, v0
	v_max_f32_e32 v0, v0, v4
	s_nop 0
	v_readlane_b32 s2, v0, 15
	s_waitcnt lgkmcnt(0)
	s_nop 0
	v_mul_f32_e32 v0, s2, v3
	s_mov_b32 s2, 0xf800000
	v_mul_f32_e32 v4, 0x4f800000, v0
	v_cmp_gt_f32_e32 vcc, s2, v0
	s_nop 1
	v_cndmask_b32_e32 v4, v0, v4, vcc
	v_sqrt_f32_e32 v5, v4
	v_lshlrev_b32_e32 v0, 3, v216
	v_add_u32_e32 v6, -1, v5
	v_add_u32_e32 v7, 1, v5
	v_fma_f32 v8, -v6, v5, v4
	v_fma_f32 v9, -v7, v5, v4
	v_cmp_ge_f32_e64 s[4:5], 0, v8
	s_nop 1
	v_cndmask_b32_e64 v5, v5, v6, s[4:5]
	v_cmp_lt_f32_e64 s[4:5], 0, v9
	s_nop 1
	v_cndmask_b32_e64 v5, v5, v7, s[4:5]
	v_mul_f32_e32 v6, 0x37800000, v5
	v_cndmask_b32_e32 v5, v5, v6, vcc
	v_cmp_class_f32_e32 vcc, v4, v232
	s_nop 1
	v_cndmask_b32_e32 v4, v5, v4, vcc
	v_mul_f32_e32 v4, 0x3e38aa3b, v4
	v_cmp_lt_f32_e32 vcc, 0, v3
	v_mov_b32_e32 v3, 0x7f800000
	s_nop 0
	v_cndmask_b32_e32 v3, v3, v4, vcc
	v_cmp_gt_i32_e32 vcc, 2, v216
	v_readfirstlane_b32 s20, v3
	s_and_saveexec_b64 s[2:3], vcc
	v_add_u32_e32 v3, s68, v0
	ds_write_b8 v3, v1
	s_or_b64 exec, exec, s[2:3]
	v_ashrrev_i32_e32 v3, 3, v216
	v_readlane_b32 s2, v255, 11
	v_and_b32_e32 v8, 24, v0
	s_lshl_b32 s19, s10, 1
	v_add_u32_e32 v3, s2, v3
	v_readlane_b32 s2, v255, 12
	v_lshrrev_b32_e32 v4, 1, v3
	v_add_u32_e32 v2, s30, v2
	v_or_b32_e32 v9, s2, v8
	s_lshl_b32 s2, s16, 24
	v_lshrrev_b32_e32 v7, 2, v216
	v_lshlrev_b32_e32 v0, 1, v216
	v_lshlrev_b32_e32 v178, 2, v219
	s_cmp_gt_u32 s63, 3
	s_cbranch_scc1 .Ldf_nopf
	v_lshlrev_b32_e32 v128, 8, v179
	v_lshl_add_u32 v128, v219, 7, v128
	v_add_u32_e32 v128, s19, v128
	v_add_u32_e32 v128, 0x7000000, v128
	v_add_co_u32_e32 v128, vcc, s17, v128
	v_mov_b32_e32 v129, s18
	v_addc_co_u32_e32 v129, vcc, 0, v129, vcc
	global_load_dword v253, v[128:129], off
.Ldf_nopf:
	s_lshl_b32 s23, s8, 1
	s_sub_i32 s4, -2.0, s2
	v_xor_b32_e32 v6, v4, v216
	v_and_or_b32 v4, v7, 7, v2
	v_lshlrev_b32_e32 v2, 7, v3
	v_and_b32_e32 v10, 32, v0
	v_and_or_b32 v0, v7, 3, v178
	s_add_u32 s2, s17, s19
	v_ashrrev_i32_e32 v3, 31, v2
	v_lshlrev_b32_e32 v7, 6, v0
	s_addc_u32 s3, s18, 0
	v_lshlrev_b32_e32 v0, 4, v6
	v_lshlrev_b32_e32 v4, 7, v4
	v_lshl_add_u64 v[2:3], v[2:3], 1, s[2:3]
	v_and_b32_e32 v0, 0x70, v0
	v_ashrrev_i32_e32 v5, 31, v4
	v_lshl_add_u64 v[2:3], v[2:3], 0, v[0:1]
	s_mov_b64 s[10:11], 0x5000000
	v_lshl_add_u64 v[180:181], v[2:3], 0, s[10:11]
	v_lshl_add_u64 v[2:3], v[4:5], 1, s[2:3]
	v_lshlrev_b32_e32 v0, 1, v9
	v_lshl_add_u64 v[2:3], v[2:3], 0, v[0:1]
	s_mov_b64 s[2:3], 0x6000000
	v_lshl_add_u64 v[182:183], v[2:3], 0, s[2:3]
	s_lshl_b32 s2, s8, 15
	s_lshr_b32 s21, s9, 6
	s_or_b32 s80, s2, 0x4000
	s_mov_b32 s3, s81
	v_readlane_b32 s8, v255, 13
	v_lshl_add_u64 v[200:201], v[180:181], 0, s[80:81]
	v_lshl_add_u64 v[194:195], v[182:183], 0, s[80:81]
	v_lshl_add_u64 v[190:191], v[180:181], 0, s[2:3]
	v_lshl_add_u64 v[184:185], v[182:183], 0, s[2:3]
	v_readlane_b32 s9, v255, 14
	v_or3_b32 v220, v7, v10, v8
	v_lshl_add_u64 v[198:199], v[200:201], 0, s[88:89]
	v_lshl_add_u64 v[192:193], v[194:195], 0, s[88:89]
	v_lshl_add_u64 v[188:189], v[190:191], 0, s[88:89]
	s_mov_b64 s[2:3], -1
	s_andn2_b64 vcc, exec, s[8:9]
	v_lshl_add_u64 v[186:187], v[184:185], 0, s[88:89]
	s_cbranch_vccnz .LBB0_424
	s_mov_b32 s2, m0
	s_mov_b32 m0, s76
	s_nop 0
	global_load_lds_dwordx4 v[200:201], off
	s_mov_b32 m0, s2
	v_readlane_b32 s3, v255, 15
	s_mov_b32 s2, m0
	s_mov_b32 m0, s3
	s_nop 0
	global_load_lds_dwordx4 v[198:199], off
	s_mov_b32 m0, s2
	v_readlane_b32 s3, v255, 16
	s_mov_b32 s2, m0
	s_mov_b32 m0, s31
	s_nop 0
	global_load_lds_dwordx4 v[194:195], off
	s_mov_b32 m0, s2
	s_cmp_eq_u32 s22, 15
	s_mov_b32 s2, m0
	s_mov_b32 m0, s3
	s_nop 0
	global_load_lds_dwordx4 v[192:193], off
	s_mov_b32 m0, s2
	v_readlane_b32 s3, v255, 17
	s_mov_b32 s2, m0
	s_mov_b32 m0, s3
	s_nop 0
	global_load_lds_dwordx4 v[190:191], off
	s_mov_b32 m0, s2
	v_readlane_b32 s3, v255, 18
	s_mov_b32 s2, m0
	s_mov_b32 m0, s3
	s_nop 0
	global_load_lds_dwordx4 v[188:189], off
	s_mov_b32 m0, s2
	v_readlane_b32 s3, v255, 19
	s_mov_b32 s2, m0
	s_mov_b32 m0, s3
	s_nop 0
	global_load_lds_dwordx4 v[184:185], off
	s_mov_b32 m0, s2
	v_readlane_b32 s3, v255, 20
	s_mov_b32 s2, m0
	s_mov_b32 m0, s3
	s_nop 0
	global_load_lds_dwordx4 v[186:187], off
	s_mov_b32 m0, s2
	s_cbranch_scc1 .LBB0_391
	s_add_i32 s80, s23, -1
	s_lshl_b64 s[2:3], s[80:81], 14
	v_lshl_add_u64 v[2:3], v[180:181], 0, s[2:3]
	v_readlane_b32 s8, v255, 21
	s_mov_b32 s5, m0
	s_mov_b32 m0, s8
	s_nop 0
	global_load_lds_dwordx4 v[2:3], off
	s_mov_b32 m0, s5
	v_lshl_add_u64 v[2:3], v[2:3], 0, s[88:89]
	v_readlane_b32 s8, v255, 22
	s_mov_b32 s5, m0
	s_mov_b32 m0, s8
	s_nop 0
	global_load_lds_dwordx4 v[2:3], off
	s_mov_b32 m0, s5
	v_lshl_add_u64 v[2:3], v[182:183], 0, s[2:3]
	v_readlane_b32 s3, v255, 23
	s_mov_b32 s2, m0
	s_mov_b32 m0, s3
	s_nop 0
	global_load_lds_dwordx4 v[2:3], off
	s_mov_b32 m0, s2
	v_lshl_add_u64 v[2:3], v[2:3], 0, s[88:89]
	v_readlane_b32 s3, v255, 24
	s_mov_b32 s2, m0
	s_mov_b32 m0, s3
	s_nop 0
	global_load_lds_dwordx4 v[2:3], off
	s_mov_b32 m0, s2

.LBB0_451:
	v_mbcnt_lo_u32_b32 v0, -1, 0
	v_mbcnt_hi_u32_b32 v0, -1, v0
	v_readlane_b32 s2, v254, 2
	v_sub_u32_e32 v0, 0, v0
	v_mov_b32_e32 v95, 0xf0000
	v_cmp_eq_u32_e32 vcc, s2, v0
	s_and_saveexec_b64 s[2:3], vcc
	s_cbranch_execz .LBB0_456
	v_mov_b32_e32 v0, s69
	ds_read_b32 v0, v0
	v_readlane_b32 s5, v254, 32
	v_readlane_b32 s8, v254, 34
	v_mov_b32_e32 v95, 0xf0000
	s_waitcnt lgkmcnt(0)
	v_readfirstlane_b32 s4, v0
	s_and_b32 s5, s4, s5
	s_cmp_eq_u32 s5, 0
	v_readlane_b32 s5, v254, 31
	s_cselect_b32 s5, s5, 15
	s_and_b32 s8, s4, s8
	s_cmp_eq_u32 s8, 0
	v_readlane_b32 s8, v254, 33
	s_cselect_b32 s5, s8, s5
	v_readlane_b32 s8, v254, 36
	s_and_b32 s8, s4, s8
	s_cmp_eq_u32 s8, 0
	v_readlane_b32 s8, v254, 35
	s_cselect_b32 s5, s8, s5
	v_readlane_b32 s8, v254, 38
	s_and_b32 s8, s4, s8
	s_cmp_eq_u32 s8, 0
	v_readlane_b32 s8, v254, 37
	s_cselect_b32 s5, s8, s5
	v_readlane_b32 s8, v254, 40
	s_and_b32 s8, s4, s8
	s_cmp_eq_u32 s8, 0
	v_readlane_b32 s8, v254, 39
	s_cselect_b32 s5, s8, s5
	v_readlane_b32 s8, v254, 42
	s_and_b32 s8, s4, s8
	s_cmp_eq_u32 s8, 0
	v_readlane_b32 s8, v254, 41
	s_cselect_b32 s5, s8, s5
	v_readlane_b32 s8, v254, 44
	s_and_b32 s8, s4, s8
	s_cmp_eq_u32 s8, 0
	v_readlane_b32 s8, v254, 43
	s_cselect_b32 s5, s8, s5
	v_readlane_b32 s8, v254, 46
	s_and_b32 s8, s4, s8
	s_cmp_eq_u32 s8, 0
	v_readlane_b32 s8, v254, 45
	s_cselect_b32 s5, s8, s5
	s_bitcmp0_b32 s4, 8
	s_cselect_b32 s4, 8, 15
	s_cmp_eq_u32 s5, 15
	s_cselect_b32 s10, s4, s5
	s_cmp_eq_u32 s10, 15
	s_cbranch_scc1 .LBB0_456
	s_mov_b64 s[8:9], exec
	v_mbcnt_lo_u32_b32 v0, s8, 0
	v_mbcnt_hi_u32_b32 v0, s9, v0
	v_cmp_eq_u32_e32 vcc, 0, v0
	s_and_saveexec_b64 s[4:5], vcc
	s_cbranch_execz .LBB0_455
	s_lshl_b32 s11, s10, 6
	s_add_i32 s11, s11, 64
	s_cmp_lt_u32 s10, 8
	s_cselect_b32 s80, s11, 0
	s_lshl_b64 s[12:13], s[80:81], 2
	v_readlane_b32 s14, v254, 51
	v_readlane_b32 s15, v254, 52
	s_add_u32 s12, s14, s12
	s_addc_u32 s13, s15, s13
	s_bcnt1_i32_b64 s8, s[8:9]
	s_waitcnt vmcnt(0)
	v_mov_b32_e32 v253, s8
	global_atomic_add v253, v1, v253, s[12:13] sc0
